# gdn_prep conv: the X=1/X=2 input rows are touched (L2 prefetch) while the X=0 rows load
# baseline (speedup 1.0000x reference)
; DI float bflo(unsigned u) { return __uint_as_float(u << 16); }
; DI float bfhi(unsigned u) { return __uint_as_float(u & 0xffff0000u); }
; DI void gdn_prep(const Params& p, int item, unsigned char* smem) {
;     ...
;         const int dch = lane & 15, sub = lane >> 4, t0 = wave * 16 + sub * 4;
; #pragma unroll
;         for (int X = 0; X < 3; ++X) {
;             const int col = X * 1024 + hd * 128 + dch * 8;
;             float xr[7][8];
; #pragma unroll
;             for (int rr = 0; rr < 7; ++rr) {
;                 const int t = t0 - 3 + rr;
;                 u32x4 v = {0u, 0u, 0u, 0u};
;                 if (n > 0 || t >= 0) v = *(const u32x4*)(pb + (size_t)(tok0 + t) * LDPB + col);
;                 xr[rr][0] = bflo(v.x); xr[rr][1] = bfhi(v.x); xr[rr][2] = bflo(v.y); xr[rr][3] = bfhi(v.y);
;                 xr[rr][4] = bflo(v.z); xr[rr][5] = bfhi(v.z); xr[rr][6] = bflo(v.w); xr[rr][7] = bfhi(v.w);
;             }
.LBB0_164:
	s_andn2_b64 vcc, exec, s[4:5]
	s_cbranch_vccnz .LBB0_157
	v_mov_b32_e32 v46, v227
	s_mov_b64 s[100:101], 0x1000
	s_and_b32 s4, s51, 0x7f
	v_lshrrev_b32_e32 v1, 2, v46
	v_ashrrev_i32_e32 v0, 6, v46
	v_and_b32_e32 v1, 12, v1
	s_and_b32 s5, s24, 0xffffe000
	s_lshl_b32 s44, s4, 6
	v_lshl_or_b32 v47, v0, 4, v1
	v_lshlrev_b32_e32 v1, 3, v46
	s_bfe_u32 s15, s51, 0x30007
	s_or_b32 s44, s5, s44
	v_and_b32_e32 v94, 0x78, v1
	s_cmp_lg_u32 s4, 0
	v_lshl_or_b32 v97, s15, 7, v94
	v_add_u32_e32 v1, -3, v47
	s_cselect_b64 s[4:5], -1, 0
	v_lshlrev_b32_e32 v116, 1, v97
	v_cmp_lt_i32_e32 vcc, 2, v47
	v_lshl_add_u64 v[20:21], s[26:27], 0, v[116:117]
	s_or_b64 s[76:77], s[4:5], vcc
	v_mov_b32_e32 v4, 0
	v_add_u32_e32 v95, s44, v1
	v_mov_b32_e32 v40, 0
	v_mov_b32_e32 v41, 0
	v_mov_b32_e32 v42, 0
	v_mov_b32_e32 v43, 0
	s_and_saveexec_b64 s[74:75], s[76:77]
	s_cbranch_execz .LBB0_167
	v_mad_i64_i32 v[2:3], s[78:79], v95, s6, v[20:21]
	global_load_dword v247, v[2:3], off offset:2048
	v_lshl_add_u64 v[222:223], v[2:3], 0, s[100:101]
	global_load_dword v247, v[222:223], off
	global_load_dwordx4 v[40:43], v[2:3], off
.LBB0_167:
	s_or_b64 exec, exec, s[74:75]
	v_add_u32_e32 v1, -2, v47
	v_cmp_lt_i32_e32 vcc, 1, v47
	s_or_b64 s[78:79], s[4:5], vcc
	v_add_u32_e32 v96, s44, v1
	v_mov_b32_e32 v8, 0
	v_mov_b32_e32 v9, 0
	v_mov_b32_e32 v10, 0
	v_mov_b32_e32 v11, 0
	s_and_saveexec_b64 s[74:75], s[78:79]
	s_cbranch_execz .LBB0_169
	v_mad_i64_i32 v[2:3], s[80:81], v96, s6, v[20:21]
	global_load_dword v247, v[2:3], off offset:2048
	v_lshl_add_u64 v[222:223], v[2:3], 0, s[100:101]
	global_load_dword v247, v[222:223], off
	global_load_dwordx4 v[8:11], v[2:3], off
.LBB0_169:
	s_or_b64 exec, exec, s[74:75]
	v_add_u32_e32 v1, -1, v47
	v_cmp_lt_i32_e32 vcc, 0, v47
	s_or_b64 s[80:81], s[4:5], vcc
	v_add_u32_e32 v98, s44, v1
	v_mov_b32_e32 v5, 0
	v_mov_b32_e32 v6, 0
	v_mov_b32_e32 v7, 0
	s_and_saveexec_b64 s[74:75], s[80:81]
	s_cbranch_execz .LBB0_171
	v_mad_i64_i32 v[2:3], vcc, v98, s6, v[20:21]
	global_load_dword v247, v[2:3], off offset:2048
	v_lshl_add_u64 v[222:223], v[2:3], 0, s[100:101]
	global_load_dword v247, v[222:223], off
	global_load_dwordx4 v[4:7], v[2:3], off
.LBB0_171:
	s_or_b64 exec, exec, s[74:75]
	v_cmp_lt_i32_e32 vcc, -1, v0
	s_or_b64 s[74:75], s[4:5], vcc
	v_mov_b32_e32 v16, 0
	v_add_u32_e32 v99, s44, v47
	v_mov_b32_e32 v12, 0
	v_mov_b32_e32 v13, 0
	v_mov_b32_e32 v14, 0
	v_mov_b32_e32 v15, 0
	s_and_saveexec_b64 s[4:5], s[74:75]
	s_cbranch_execz .LBB0_173
	v_mad_i64_i32 v[0:1], vcc, v99, s6, v[20:21]
	global_load_dword v247, v[0:1], off offset:2048
	v_lshl_add_u64 v[222:223], v[0:1], 0, s[100:101]
	global_load_dword v247, v[222:223], off
	global_load_dwordx4 v[12:15], v[0:1], off
.LBB0_173:
	s_or_b64 exec, exec, s[4:5]
	v_or_b32_e32 v0, 1, v47
	v_add_u32_e32 v100, s44, v0
	v_mov_b32_e32 v17, 0
	v_mov_b32_e32 v18, 0
	v_mov_b32_e32 v19, 0
	s_and_saveexec_b64 s[4:5], s[74:75]
	s_cbranch_execz .LBB0_175
	v_mad_i64_i32 v[0:1], vcc, v100, s6, v[20:21]
	global_load_dword v247, v[0:1], off offset:2048
	v_lshl_add_u64 v[222:223], v[0:1], 0, s[100:101]
	global_load_dword v247, v[222:223], off
	global_load_dwordx4 v[16:19], v[0:1], off
.LBB0_175:
	s_or_b64 exec, exec, s[4:5]
	v_or_b32_e32 v1, 2, v47
	v_mov_b32_e32 v0, 0
	v_add_u32_e32 v101, s44, v1
	v_mov_b32_e32 v36, 0
	v_mov_b32_e32 v37, 0
	v_mov_b32_e32 v38, 0
	v_mov_b32_e32 v39, 0
	s_and_saveexec_b64 s[4:5], s[74:75]
	s_cbranch_execz .LBB0_177
	v_mad_i64_i32 v[2:3], vcc, v101, s6, v[20:21]
	global_load_dword v247, v[2:3], off offset:2048
	v_lshl_add_u64 v[222:223], v[2:3], 0, s[100:101]
	global_load_dword v247, v[222:223], off
	global_load_dwordx4 v[36:39], v[2:3], off
.LBB0_177:
	s_or_b64 exec, exec, s[4:5]
	v_or_b32_e32 v1, 3, v47
	v_add_u32_e32 v102, s44, v1
	v_mov_b32_e32 v1, 0
	v_mov_b32_e32 v2, 0
	v_mov_b32_e32 v3, 0
	s_and_saveexec_b64 s[4:5], s[74:75]
	s_cbranch_execz .LBB0_179
	v_mad_i64_i32 v[0:1], vcc, v102, s6, v[20:21]
	global_load_dword v247, v[0:1], off offset:2048
	v_lshl_add_u64 v[222:223], v[0:1], 0, s[100:101]
	global_load_dword v247, v[222:223], off
	global_load_dwordx4 v[0:3], v[0:1], off

; __global__ void __launch_bounds__(512, 2) hymba_fwd(Params pin) {
;     extern __shared__ __attribute__((aligned(16))) unsigned char smem[];
;     Params p = pin;
;     p.wave8 = __builtin_amdgcn_readfirstlane((int)(threadIdx.x >> 6));
	.amdhsa_kernel _Z9hymba_fwd6Params
		.amdhsa_group_segment_fixed_size 0
		.amdhsa_private_segment_fixed_size 0
		.amdhsa_kernarg_size 408
		.amdhsa_user_sgpr_count 2
		.amdhsa_user_sgpr_dispatch_ptr 0
		.amdhsa_user_sgpr_queue_ptr 0
		.amdhsa_user_sgpr_kernarg_segment_ptr 1
		.amdhsa_user_sgpr_dispatch_id 0
		.amdhsa_user_sgpr_kernarg_preload_length 0
		.amdhsa_user_sgpr_kernarg_preload_offset 0
		.amdhsa_user_sgpr_private_segment_size 0
		.amdhsa_uses_dynamic_stack 0
		.amdhsa_enable_private_segment 0
		.amdhsa_system_sgpr_workgroup_id_x 1
		.amdhsa_system_sgpr_workgroup_id_y 0
		.amdhsa_system_sgpr_workgroup_id_z 0
		.amdhsa_system_sgpr_workgroup_info 0
		.amdhsa_system_vgpr_workitem_id 2
		.amdhsa_next_free_vgpr 248
		.amdhsa_next_free_sgpr 102
		.amdhsa_accum_offset 248
		.amdhsa_reserve_vcc 1
		.amdhsa_float_round_mode_32 0
		.amdhsa_float_round_mode_16_64 0
		.amdhsa_float_denorm_mode_32 3
		.amdhsa_float_denorm_mode_16_64 3
		.amdhsa_dx10_clamp 1
		.amdhsa_ieee_mode 1
		.amdhsa_fp16_overflow 0
		.amdhsa_tg_split 0
		.amdhsa_exception_fp_ieee_invalid_op 0
		.amdhsa_exception_fp_denorm_src 0
		.amdhsa_exception_fp_ieee_div_zero 0
		.amdhsa_exception_fp_ieee_overflow 0
		.amdhsa_exception_fp_ieee_underflow 0
		.amdhsa_exception_fp_ieee_inexact 0
		.amdhsa_exception_int_div_zero 0
	.end_amdhsa_kernel

; __global__ void __launch_bounds__(512, 2) hymba_fwd(Params pin) {
amdhsa.kernels:
  - .agpr_count:     0
    .args:
      - .offset:         0
        .size:           152
        .value_kind:     by_value
      - .offset:         152
        .size:           4
        .value_kind:     hidden_block_count_x
      - .offset:         156
        .size:           4
        .value_kind:     hidden_block_count_y
      - .offset:         160
        .size:           4
        .value_kind:     hidden_block_count_z
      - .offset:         164
        .size:           2
        .value_kind:     hidden_group_size_x
      - .offset:         166
        .size:           2
        .value_kind:     hidden_group_size_y
      - .offset:         168
        .size:           2
        .value_kind:     hidden_group_size_z
      - .offset:         170
        .size:           2
        .value_kind:     hidden_remainder_x
      - .offset:         172
        .size:           2
        .value_kind:     hidden_remainder_y
      - .offset:         174
        .size:           2
        .value_kind:     hidden_remainder_z
      - .offset:         192
        .size:           8
        .value_kind:     hidden_global_offset_x
      - .offset:         200
        .size:           8
        .value_kind:     hidden_global_offset_y
      - .offset:         208
        .size:           8
        .value_kind:     hidden_global_offset_z
      - .offset:         216
        .size:           2
        .value_kind:     hidden_grid_dims
      - .offset:         240
        .size:           8
        .value_kind:     hidden_multigrid_sync_arg
      - .offset:         272
        .size:           4
        .value_kind:     hidden_dynamic_lds_size
    .group_segment_fixed_size: 0
    .kernarg_segment_align: 8
    .kernarg_segment_size: 408
    .language:       OpenCL C
    .language_version:
      - 2
      - 0
    .max_flat_workgroup_size: 512
    .name:           _Z9hymba_fwd6Params
    .private_segment_fixed_size: 0
    .sgpr_count:     108
    .sgpr_spill_count: 167
    .symbol:         _Z9hymba_fwd6Params.kd
    .uniform_work_group_size: 1
    .uses_dynamic_stack: false
    .vgpr_count:     248
    .vgpr_spill_count: 0
    .wavefront_size: 64
